# no cooperative-groups syncs left: A->B layer 0 uses magic-flag barrier, J->layer 1 uses flat counter
# speedup vs baseline: 1.0355x; 1.0037x over previous
; __global__ void __launch_bounds__(512, 2) hybrid_fwd(Params P) {
;     ...
;         grid.sync();
.LBB0_413:
	s_or_b64 exec, exec, s[4:5]
	s_waitcnt vmcnt(0) lgkmcnt(0)
	s_barrier
	s_mov_b64 s[4:5], exec
	v_readlane_b32 s6, v255, 5
	v_readlane_b32 s7, v255, 6
	s_and_b64 s[6:7], s[4:5], s[6:7]
	s_xor_b64 s[4:5], s[6:7], s[4:5]
	s_mov_b64 exec, s[6:7]
	s_cbranch_execz .LBB0_423
	v_readlane_b32 s8, v255, 17
	s_cmp_eq_u32 s8, 0
	s_cbranch_scc1 .Lgb_flag_0
	s_lshl_b32 s8, s2, 2
	v_mov_b32_e32 v1, s8
	v_mov_b32_e32 v0, 0
	global_store_dword v1, v0, s[58:59] offset:1024
	s_cmp_lg_u32 s2, 0
	s_cbranch_scc1 .Lgb_clr_0
	global_store_dword v0, v0, s[58:59] offset:2048
.Lgb_clr_0:
	buffer_wbl2 sc1
	s_waitcnt vmcnt(0)
	v_readlane_b32 s8, v255, 17
	v_mov_b32_e32 v1, 0
	v_mov_b32_e32 v0, 1
	s_lshl_b32 s8, s8, 5
	s_add_u32 s6, s58, s8
	s_addc_u32 s7, s59, 0
	s_mov_b32 s10, 0
	global_atomic_add v1, v0, s[6:7] offset:64

; __global__ void __launch_bounds__(512, 2) hybrid_fwd(Params P) {
;     ...
;         grid.sync();
.Lgb_flag_0:
	buffer_wbl2 sc1
	s_waitcnt vmcnt(0)
	s_lshl_b32 s8, s2, 2
	v_mov_b32_e32 v0, 0x1b873593
	v_mov_b32_e32 v1, s8
	global_atomic_swap v1, v0, s[58:59] offset:1024
	s_cmp_lg_u32 s2, 0
	s_cbranch_scc1 .Lgb_flag_wait
	s_mov_b64 s[6:7], exec
	s_mov_b64 exec, -1
	v_mov_b32_e32 v0, 0x1b873593
	v_lshlrev_b32_e32 v1, 4, v146
	s_mov_b32 s10, 0
.Lgb_flag_poll:
	global_load_dwordx4 v[2:5], v1, s[58:59] offset:1024 sc1
	s_waitcnt vmcnt(0)
	v_cmp_eq_u32_e64 s[8:9], v2, v0
	v_cmp_eq_u32_e64 s[12:13], v3, v0
	s_and_b64 s[8:9], s[8:9], s[12:13]
	v_cmp_eq_u32_e64 s[12:13], v4, v0
	s_and_b64 s[8:9], s[8:9], s[12:13]
	v_cmp_eq_u32_e64 s[12:13], v5, v0
	s_and_b64 s[8:9], s[8:9], s[12:13]
	s_cmp_eq_u64 s[8:9], -1
	s_cbranch_scc1 .Lgb_flag_all
	s_add_u32 s10, s10, 1
	s_cmp_gt_u32 s10, 0x40000
	s_cbranch_scc1 .Lgb_flag_all
	s_sleep 1
	s_branch .Lgb_flag_poll
.Lgb_flag_all:
	s_mov_b64 exec, s[6:7]
	v_mov_b32_e32 v1, 0
	global_atomic_swap v1, v0, s[58:59] offset:2048
.Lgb_flag_wait:
	v_mov_b32_e32 v1, 0
	s_mov_b32 s10, 0
.Lgb_go_poll:
	global_load_dword v2, v1, s[58:59] offset:2048 sc1
	s_waitcnt vmcnt(0)
	v_readfirstlane_b32 s8, v2
	s_cmp_eq_u32 s8, 0x1b873593
	s_cbranch_scc1 .Lgb_go_done
	s_add_u32 s10, s10, 1
	s_cmp_gt_u32 s10, 0x40000
	s_cbranch_scc1 .Lgb_go_done
	s_sleep 1
	s_branch .Lgb_go_poll

; __global__ void __launch_bounds__(512, 2) hybrid_fwd(Params P) {
;     ...
;         if (layer == 0) grid.sync();
.LBB0_1307:
	s_waitcnt vmcnt(0) lgkmcnt(0)
	s_barrier
	s_mov_b64 s[4:5], exec
	v_readlane_b32 s6, v255, 5
	v_readlane_b32 s7, v255, 6
	s_and_b64 s[6:7], s[4:5], s[6:7]
	s_mov_b64 exec, s[6:7]
	s_cbranch_execnz .LBB0_1308
	s_getpc_b64 s[98:99]

; __global__ void __launch_bounds__(512, 2) hybrid_fwd(Params P) {
;     ...
;         if (layer == 0) grid.sync();
.LBB0_1308:
	buffer_wbl2 sc1
	s_waitcnt vmcnt(0)
	v_readlane_b32 s8, v255, 17
	v_mov_b32_e32 v1, 0
	v_mov_b32_e32 v0, 1
	s_lshl_b32 s8, s8, 5
	s_add_u32 s6, s58, s8
	s_addc_u32 s7, s59, 0
	s_mov_b32 s10, 0
	global_atomic_add v1, v0, s[6:7] offset:128
.Lgb_poll_16:
	global_load_dword v2, v1, s[6:7] offset:128 sc1
	s_waitcnt vmcnt(0)
	v_readfirstlane_b32 s8, v2
	s_cmp_ge_u32 s8, s69
	s_cbranch_scc1 .Lgb_done_16
	s_add_u32 s10, s10, 1
	s_cmp_gt_u32 s10, 0x40000
	s_cbranch_scc1 .Lgb_done_16
	s_sleep 1
	s_branch .Lgb_poll_16
.Lgb_done_16:
	s_getpc_b64 s[98:99]
